# static s_setprio 1 for waves 4-7 inside the P2 task loops (prompt attention and gMLP; reset to 0 at loop exit): the younger half is also the half with the longer causal MFMA loops in gMLP step C
# baseline (speedup 1.0000x reference)
; __device__ __forceinline__ void attn_run(LAS unsigned char* lds, const Params& p, const bf16_t* P, bf16_t* Y, float* ssa, int l, int t0, int t1, int wave) {
;     ...
;     for (int t = t0; t < t1; ++t) {
;         const int c = t & 31, bk = t >> 5, kvh = bk & 3, b = bk >> 2;
;         const bool cont = (bk == prev_bk) && (c == prev_c + 1);
.LBB0_325:
	s_cmp_lt_u32 s6, 0x100
	s_cbranch_scc1 .Lmy_prio_skip0
	s_setprio 1

; __device__ __forceinline__ void block_wait(unsigned* cnt, unsigned want) {
;     if (threadIdx.x == 0) {
;         unsigned spins = 0;
;         while (__hip_atomic_load(cnt, __ATOMIC_RELAXED, __HIP_MEMORY_SCOPE_AGENT) < want) { __builtin_amdgcn_s_sleep(4); if (++spins > (1u << 24)) break; }
;         __builtin_amdgcn_fence(__ATOMIC_ACQUIRE, "agent"); asm volatile("s_waitcnt vmcnt(0)" ::: "memory");
; __device__ __forceinline__ void p2_phase(LAS unsigned char* lds, const Params& p, int l, int tid, int wave, int lane, int bid, int G) {
;     ...
;     if (bid < 32) {
;         block_wait(CNT, 256u);
.LBB0_361:
	s_setprio 0
	v_readlane_b32 s0, v253, 19
	v_readlane_b32 s1, v253, 20
	s_andn2_b64 vcc, exec, s[0:1]
	s_cbranch_vccnz .LBB0_407
	v_readlane_b32 s4, v251, 4
	v_readlane_b32 s5, v251, 5
	s_and_saveexec_b64 s[0:1], s[4:5]
	s_cbranch_execz .LBB0_377
	s_mov_b32 s7, 0x1000000
	s_branch .LBB0_366

; #define LAS __attribute__((address_space(3)))
; __device__ __forceinline__ int lane_fresh() { int l; asm volatile("v_mbcnt_lo_u32_b32 %0, -1, 0\n\tv_mbcnt_hi_u32_b32 %0, -1, %0" : "=v"(l)); return l; }
; __device__ __forceinline__ void gmlp_task(LAS unsigned char* lds, const Params& p, const bf16_t* P, bf16_t* Y, const float* svg, float* ssb, int l, bool sample, int b, int g, int q, int tid, int wave, int lane, bool load_ws = true) {
;     lane = lane_fresh(); tid = wave * 64 + lane;
;     LAS bf16_t* WSL = (LAS bf16_t*)(lds + L_WS);
;     LAS f32x2* MUR = (LAS f32x2*)(lds + L_MUR);
;     if (load_ws) {
;         const float* wsp = p.w_spatial + (size_t)(l * 16 + g) * 128 * 128;
; __device__ __forceinline__ void p2_phase(LAS unsigned char* lds, const Params& p, int l, int tid, int wave, int lane, int bid, int G) {
;     ...
;     for (int u = ug0; u < ug1; ++u)
;         gmlp_task(lds, p, P, Y, SVG, SSB, l, false, (u >> 2) & 15, u >> 6, u & 3, tid, wave, lane, u == ug0 || (u >> 6) != ((u - 1) >> 6));
.LBB0_446:
	s_setprio 0
	s_cmp_ge_i32 s20, s21
	s_cbranch_scc1 .LBB0_510
	v_readlane_b32 s0, v255, 13
	v_readlane_b32 s1, v255, 14
	s_lshl_b32 s44, s0, 10
	s_lshl_b32 s7, s0, 4
	s_lshl_b32 s22, s0, 11
	s_lshl_b64 s[0:1], s[44:45], 2
	s_add_u32 s23, s60, s0
	s_addc_u32 s24, s61, s1
	s_add_u32 s25, s58, s0
	s_addc_u32 s26, s59, s1
	s_mov_b32 s29, s20
	s_branch .LBB0_449

; __device__ __forceinline__ void block_wait(unsigned* cnt, unsigned want) {
;     if (threadIdx.x == 0) {
;         unsigned spins = 0;
;         while (__hip_atomic_load(cnt, __ATOMIC_RELAXED, __HIP_MEMORY_SCOPE_AGENT) < want) { __builtin_amdgcn_s_sleep(4); if (++spins > (1u << 24)) break; }
; __device__ __forceinline__ void p2_phase(LAS unsigned char* lds, const Params& p, int l, int tid, int wave, int lane, int bid, int G) {
;     ...
;     attn_run(lds, p, P, Y, SSA, l, tsplit, ta1, wave);
;     for (int u = ug0; u < ug1; ++u)
;         gmlp_task(lds, p, P, Y, SVG, SSB, l, false, (u >> 2) & 15, u >> 6, u & 3, tid, wave, lane, u == ug0 || (u >> 6) != ((u - 1) >> 6));
;     if (bid >= 32 && bid < ngemm) {
;         const int idx = bid - 32, tile = idx / 22;
;         block_wait(CNT + 64 * (1 + tile), 8u);
.LBB0_510:
	s_setprio 0
	v_readlane_b32 s0, v253, 19
	v_readlane_b32 s1, v253, 20
	s_or_b64 s[0:1], s[0:1], s[38:39]
	s_andn2_b64 vcc, exec, s[0:1]
	s_cbranch_vccz .LBB0_567
	v_readlane_b32 s4, v251, 4
	v_readlane_b32 s5, v251, 5
	s_and_saveexec_b64 s[0:1], s[4:5]
	s_cbranch_execz .LBB0_526
	v_readlane_b32 s4, v255, 5
	s_add_u32 s8, s8, s4
	s_addc_u32 s9, s9, 0
	s_mov_b32 s7, 0x1000000
	s_branch .LBB0_515
